# attention tile loop: loop-top scalar set-up issued in the shadow of the three tail MFMAs; second half-step fills the K-fragment LDS latency with four more exps
# speedup vs baseline: 1.0043x; 1.0009x over previous
.LBB0_421:
	s_lshl_b64 s[4:5], s[4:5], 1
	v_lshl_add_u64 v[0:1], v[186:187], 0, s[4:5]
	global_load_dwordx4 v[160:163], v[0:1], off
	global_load_dwordx4 v[164:167], v[0:1], off offset:32
	global_load_dwordx4 v[168:171], v[0:1], off offset:64
	global_load_dwordx4 v[172:175], v[0:1], off offset:96
	s_xor_b64 s[30:31], s[6:7], -1
	s_add_u32 s36, s73, s4
	s_addc_u32 s37, s74, s5
	v_lshl_add_u64 v[0:1], v[180:181], 1, s[36:37]
	s_mov_b32 s4, m0
	s_mov_b32 m0, s43
	s_nop 0
	global_load_lds_dwordx4 v[0:1], off
	s_mov_b32 m0, s4
	v_lshl_add_u64 v[0:1], v[0:1], 0, s[22:23]
	s_mov_b32 s4, m0
	s_mov_b32 m0, s64
	s_nop 0
	global_load_lds_dwordx4 v[0:1], off
	s_mov_b32 m0, s4
	v_add_u32_e32 v4, 0, v206
	s_mov_b32 s4, m0
	s_mov_b32 m0, s65
	s_nop 0
	global_load_lds_dwordx4 v[190:191], off
	s_mov_b32 m0, s4
	v_add_u32_e32 v8, 0, v207
	s_mov_b32 s4, m0
	s_mov_b32 m0, s66
	s_nop 0
	global_load_lds_dwordx4 v[192:193], off
	s_mov_b32 m0, s4
	s_waitcnt vmcnt(0)
	s_barrier
	v_add_u32_e32 v9, 0, v209
	s_mov_b32 s4, 0
	s_mov_b32 s5, s4
	s_mov_b32 s6, s4
	s_mov_b32 s7, s4
	s_mov_b32 s8, s4
	s_mov_b32 s9, s4
	s_mov_b32 s10, s4
	s_mov_b32 s11, s4
	s_mov_b32 s12, s4
	s_mov_b32 s13, s4
	s_mov_b32 s14, s4
	s_mov_b32 s15, s4
	s_mov_b32 s16, s4
	s_mov_b32 s17, s4
	s_mov_b32 s18, s4
	s_mov_b32 s19, s4
	v_mov_b32_e32 v196, 0
	s_movk_i32 s77, 0x4000
	s_movk_i32 s76, 0x2000
	s_mov_b32 s75, 0x20000
	s_mov_b64 s[38:39], s[28:29]
	s_waitcnt vmcnt(0)
	ds_read_b128 v[0:3], v4
	ds_read_b128 v[4:7], v4 offset:4096
	s_waitcnt lgkmcnt(1)
	v_mfma_f32_32x32x16_bf16 v[64:79], v[0:3], v[160:163], 0
	s_waitcnt lgkmcnt(0)
	v_mfma_f32_32x32x16_bf16 v[80:95], v[4:7], v[160:163], 0
	ds_read_b128 v[0:3], v8
	ds_read_b128 v[4:7], v8 offset:4096
	v_add_u32_e32 v8, 0, v208
	s_waitcnt lgkmcnt(1)
	v_mfma_f32_32x32x16_bf16 v[64:79], v[0:3], v[164:167], v[64:79]
	ds_read_b128 v[0:3], v8
	s_waitcnt lgkmcnt(1)
	v_mfma_f32_32x32x16_bf16 v[80:95], v[4:7], v[164:167], v[80:95]
	ds_read_b128 v[4:7], v8 offset:4096
	s_waitcnt lgkmcnt(1)
	v_mfma_f32_32x32x16_bf16 v[64:79], v[0:3], v[168:171], v[64:79]
	ds_read_b128 v[0:3], v9
	s_waitcnt lgkmcnt(1)
	v_mfma_f32_32x32x16_bf16 v[80:95], v[4:7], v[168:171], v[80:95]
	ds_read_b128 v[4:7], v9 offset:4096
	s_waitcnt lgkmcnt(1)
	v_mfma_f32_32x32x16_bf16 v[64:79], v[0:3], v[172:175], v[64:79]
	s_waitcnt lgkmcnt(0)
	v_mfma_f32_32x32x16_bf16 v[80:95], v[4:7], v[172:175], v[80:95]
	s_nop 9
	v_max_f32_e32 v0, v65, v65
	v_max_f32_e32 v1, v64, v64
	v_max_f32_e32 v0, v1, v0
	v_max3_f32 v0, v0, v66, v67
	v_max3_f32 v0, v0, v68, v69
	v_max3_f32 v0, v0, v70, v71
	v_max3_f32 v0, v0, v72, v73
	v_max3_f32 v0, v0, v74, v75
	v_max3_f32 v0, v0, v76, v77
	v_max3_f32 v0, v0, v78, v79
	v_max3_f32 v0, v0, v80, v81
	v_max3_f32 v0, v0, v82, v83
	v_max3_f32 v0, v0, v84, v85
	v_max3_f32 v0, v0, v86, v87
	v_max3_f32 v0, v0, v88, v89
	v_max3_f32 v0, v0, v90, v91
	v_max3_f32 v0, v0, v92, v93
	v_max3_f32 v197, v0, v94, v95
	ds_bpermute_b32 v96, v204, v197
	v_mov_b64_e32 v[0:1], s[4:5]
	v_mov_b64_e32 v[14:15], s[18:19]
	v_mov_b64_e32 v[2:3], s[6:7]
	v_mov_b64_e32 v[4:5], s[8:9]
	s_waitcnt lgkmcnt(0)
	v_max_f32_e32 v96, v96, v96
	v_max_f32_e32 v195, v197, v96
	v_mov_b64_e32 v[6:7], s[10:11]
	v_mov_b64_e32 v[8:9], s[12:13]
	v_mov_b64_e32 v[10:11], s[14:15]
	v_mov_b64_e32 v[12:13], s[16:17]
	v_mov_b64_e32 v[30:31], v[14:15]
	v_mov_b64_e32 v[46:47], v[14:15]
	v_mov_b64_e32 v[62:63], v[14:15]
	v_sub_f32_e32 v112, v64, v195
	v_xor_b32_e32 v64, 0x80000000, v195
	v_mov_b64_e32 v[28:29], v[12:13]
	v_mov_b64_e32 v[26:27], v[10:11]
	v_mov_b64_e32 v[24:25], v[8:9]
	v_mov_b64_e32 v[22:23], v[6:7]
	v_mov_b64_e32 v[20:21], v[4:5]
	v_mov_b64_e32 v[18:19], v[2:3]
	v_mov_b64_e32 v[16:17], v[0:1]
	v_mov_b64_e32 v[44:45], v[12:13]
	v_mov_b64_e32 v[42:43], v[10:11]
	v_mov_b64_e32 v[40:41], v[8:9]
	v_mov_b64_e32 v[38:39], v[6:7]
	v_mov_b64_e32 v[36:37], v[4:5]
	v_mov_b64_e32 v[34:35], v[2:3]
	v_mov_b64_e32 v[32:33], v[0:1]
	v_mov_b64_e32 v[60:61], v[12:13]
	v_mov_b64_e32 v[58:59], v[10:11]
	v_mov_b64_e32 v[56:57], v[8:9]
	v_mov_b64_e32 v[54:55], v[6:7]
	v_mov_b64_e32 v[52:53], v[4:5]
	v_mov_b64_e32 v[50:51], v[2:3]
	v_mov_b64_e32 v[48:49], v[0:1]
	v_sub_f32_e32 v127, v79, v195
	v_sub_f32_e32 v126, v78, v195
	v_sub_f32_e32 v125, v77, v195
	v_sub_f32_e32 v124, v76, v195
	v_sub_f32_e32 v123, v75, v195
	v_sub_f32_e32 v122, v74, v195
	v_sub_f32_e32 v121, v73, v195
	v_sub_f32_e32 v120, v72, v195
	v_sub_f32_e32 v119, v71, v195
	v_sub_f32_e32 v118, v70, v195
	v_sub_f32_e32 v117, v69, v195
	v_sub_f32_e32 v116, v68, v195
	v_sub_f32_e32 v115, v67, v195
	v_sub_f32_e32 v114, v66, v195
	v_sub_f32_e32 v113, v65, v195
	v_sub_f32_e32 v159, v95, v195
	v_sub_f32_e32 v158, v94, v195
	v_sub_f32_e32 v157, v93, v195
	v_sub_f32_e32 v156, v92, v195
	v_sub_f32_e32 v155, v91, v195
	v_sub_f32_e32 v154, v90, v195
	v_sub_f32_e32 v153, v89, v195
	v_sub_f32_e32 v152, v88, v195
	v_sub_f32_e32 v151, v87, v195
	v_sub_f32_e32 v150, v86, v195
	v_sub_f32_e32 v149, v85, v195
	v_sub_f32_e32 v148, v84, v195
	v_sub_f32_e32 v147, v83, v195
	v_sub_f32_e32 v146, v82, v195
	v_sub_f32_e32 v145, v81, v195
	v_sub_f32_e32 v144, v80, v195
	v_mov_b32_e32 v65, v64
	v_mov_b32_e32 v66, v64
	v_mov_b32_e32 v67, v64
	v_mov_b32_e32 v68, v64
	v_mov_b32_e32 v69, v64
	v_mov_b32_e32 v70, v64
	v_mov_b32_e32 v71, v64
	v_mov_b32_e32 v72, v64
	v_mov_b32_e32 v73, v64
	v_mov_b32_e32 v74, v64
	v_mov_b32_e32 v75, v64
	v_mov_b32_e32 v76, v64
	v_mov_b32_e32 v77, v64
	v_mov_b32_e32 v78, v64
	v_mov_b32_e32 v79, v64
	s_cmp_gt_u32 s4, 33
	s_cselect_b64 s[6:7], -1, 0
	s_cmp_lt_u32 s4, 34
	s_cselect_b32 s20, s75, 0x230000
	s_lshl_b64 s[8:9], s[20:21], 1
	s_add_u32 s8, s36, s8
	s_addc_u32 s9, s37, s9
	s_add_i32 s5, s77, 0
	s_branch .LBB0_424

.LBB0_423:
	v_add_u32_e32 v81, s5, v206
	ds_read_b128 v[82:85], v81
	ds_read_b128 v[86:89], v81 offset:4096
	v_add_u32_e32 v90, s5, v207
	v_add_u32_e32 v94, s5, v208
	v_exp_f32_e32 v128, v128
	v_exp_f32_e32 v129, v129
	v_exp_f32_e32 v152, v96
	v_exp_f32_e32 v153, v97
	v_exp_f32_e32 v108, v108
	v_exp_f32_e32 v109, v109
	v_exp_f32_e32 v110, v110
	v_exp_f32_e32 v111, v111
	v_add_f32_e32 v154, v153, v152
	v_add_u32_e32 v81, s5, v209
	s_waitcnt lgkmcnt(1)
	v_mfma_f32_32x32x16_bf16 v[112:127], v[82:85], v[160:163], v[64:79]
	ds_read_b128 v[82:85], v90
	ds_read_b128 v[90:93], v90 offset:4096
	ds_read_b128 v[144:147], v94
	ds_read_b128 v[148:151], v94 offset:4096
	s_add_i32 s4, s4, 2
	s_waitcnt lgkmcnt(4)
	v_mfma_f32_32x32x16_bf16 v[216:231], v[86:89], v[160:163], v[64:79]
	ds_read_b128 v[86:89], v81
	ds_read_b128 v[94:97], v81 offset:4096
	v_add_f32_e32 v81, v129, v128
	v_add_f32_e32 v81, v154, v81
	v_cvt_pk_bf16_f32 v128, v128, v129
	s_add_i32 s5, s76, s77
	s_cmpk_eq_i32 s5, 0x2000
	s_waitcnt lgkmcnt(5)
	v_mfma_f32_32x32x16_bf16 v[112:127], v[82:85], v[164:167], v[112:127]
	v_exp_f32_e32 v83, v130
	v_exp_f32_e32 v84, v131
	v_exp_f32_e32 v85, v98
	v_exp_f32_e32 v98, v99
	v_exp_f32_e32 v99, v103
	v_cvt_pk_bf16_f32 v129, v83, v84
	v_exp_f32_e32 v103, v137
	s_waitcnt lgkmcnt(4)
	v_mfma_f32_32x32x16_bf16 v[216:231], v[90:93], v[164:167], v[216:231]
	v_add_f32_e32 v90, v84, v83
	v_add_f32_e32 v91, v98, v85
	v_add_f32_e32 v90, v91, v90
	v_add_f32_e32 v81, v90, v81
	v_exp_f32_e32 v90, v132
	v_exp_f32_e32 v91, v133
	v_exp_f32_e32 v92, v100
	v_exp_f32_e32 v93, v101
	s_waitcnt lgkmcnt(3)
	v_mfma_f32_32x32x16_bf16 v[112:127], v[144:147], v[168:171], v[112:127]
	v_cvt_pk_bf16_f32 v83, v85, v98
	v_add_f32_e32 v84, v91, v90
	v_add_f32_e32 v85, v93, v92
	v_add_f32_e32 v84, v85, v84
	v_cvt_pk_bf16_f32 v130, v90, v91
	v_exp_f32_e32 v85, v134
	v_exp_f32_e32 v90, v135
	s_waitcnt lgkmcnt(2)
	v_mfma_f32_32x32x16_bf16 v[216:231], v[148:151], v[168:171], v[216:231]
	v_exp_f32_e32 v98, v102
	v_add_f32_e32 v81, v84, v81
	v_add_f32_e32 v91, v90, v85
	v_exp_f32_e32 v102, v136
	v_exp_f32_e32 v136, v104
	v_exp_f32_e32 v137, v105
	v_cvt_pk_bf16_f32 v84, v92, v93
	s_waitcnt lgkmcnt(1)
	v_mfma_f32_32x32x16_bf16 v[112:127], v[86:89], v[172:175], v[112:127]
	v_add_f32_e32 v86, v99, v98
	v_add_f32_e32 v86, v86, v91
	v_add_f32_e32 v81, v86, v81
	ds_read_b64_tr_b16 v[86:87], v213 offset:40960
	ds_read_b64_tr_b16 v[88:89], v213 offset:43008
	v_cvt_pk_bf16_f32 v131, v85, v90
	v_add_f32_e32 v104, v103, v102
	v_add_f32_e32 v105, v137, v136
	s_waitcnt lgkmcnt(2)
	v_mfma_f32_32x32x16_bf16 v[216:231], v[94:97], v[172:175], v[216:231]
	ds_read_b64_tr_b16 v[90:91], v214 offset:40960
	ds_read_b64_tr_b16 v[92:93], v214 offset:43008
	ds_read_b64_tr_b16 v[94:95], v213 offset:45056
	ds_read_b64_tr_b16 v[96:97], v213 offset:47104
	v_cvt_pk_bf16_f32 v85, v98, v99
	v_cvt_pk_bf16_f32 v82, v152, v153
	s_cselect_b32 s8, s71, 0x2000
	s_cmpk_lg_i32 s5, 0x6000
	s_cselect_b32 s77, s8, 0
	s_add_u32 s38, s38, 0x40000
	s_waitcnt lgkmcnt(2)
	v_mfma_f32_32x32x16_bf16 v[32:47], v[90:93], v[128:131], v[32:47]
	v_add_f32_e32 v90, v105, v104
	v_add_f32_e32 v81, v90, v81
	v_cvt_pk_bf16_f32 v90, v102, v103
	v_exp_f32_e32 v91, v138
	v_exp_f32_e32 v92, v139
	v_exp_f32_e32 v138, v106
	v_exp_f32_e32 v106, v140
	v_mfma_f32_32x32x16_bf16 v[48:63], v[86:89], v[128:131], v[48:63]
	ds_read_b64_tr_b16 v[86:87], v215 offset:40960
	ds_read_b64_tr_b16 v[88:89], v215 offset:43008
	ds_read_b64_tr_b16 v[98:99], v214 offset:45056
	ds_read_b64_tr_b16 v[100:101], v214 offset:47104
	ds_read_b64_tr_b16 v[102:103], v248 offset:40960
	ds_read_b64_tr_b16 v[104:105], v248 offset:43008
	ds_read_b64_tr_b16 v[132:133], v215 offset:45056
	ds_read_b64_tr_b16 v[134:135], v215 offset:47104
	v_exp_f32_e32 v139, v107
	v_mov_b64_e32 v[158:159], v[230:231]
	s_addc_u32 s39, s39, 0
	s_add_i32 s75, s75, 0x20000
	s_and_b64 vcc, exec, s[6:7]
	s_waitcnt lgkmcnt(2)
	v_mfma_f32_32x32x16_bf16 v[0:15], v[102:105], v[128:131], v[0:15]
	v_exp_f32_e32 v102, v141
	v_exp_f32_e32 v103, v142
	v_exp_f32_e32 v104, v143
	v_add_f32_e32 v105, v92, v91
	v_cvt_pk_bf16_f32 v91, v91, v92
	v_cvt_pk_bf16_f32 v92, v106, v102
	v_cvt_pk_bf16_f32 v93, v103, v104
	v_mfma_f32_32x32x16_bf16 v[16:31], v[86:89], v[128:131], v[16:31]
	ds_read_b64_tr_b16 v[86:87], v248 offset:45056
	ds_read_b64_tr_b16 v[88:89], v248 offset:47104
	v_mov_b64_e32 v[156:157], v[228:229]
	v_mov_b64_e32 v[154:155], v[226:227]
	v_mov_b64_e32 v[152:153], v[224:225]
	v_mov_b64_e32 v[150:151], v[222:223]
	v_mov_b64_e32 v[148:149], v[220:221]
	v_mov_b64_e32 v[146:147], v[218:219]
	v_mfma_f32_32x32x16_bf16 v[48:63], v[94:97], v[90:93], v[48:63]
	v_add_f32_e32 v94, v139, v138
	v_add_f32_e32 v94, v94, v105
	v_add_f32_e32 v81, v94, v81
	v_add_f32_e32 v94, v102, v106
	v_add_f32_e32 v95, v109, v108
	v_add_f32_e32 v94, v95, v94
	v_add_f32_e32 v81, v94, v81
	v_mfma_f32_32x32x16_bf16 v[32:47], v[98:101], v[90:93], v[32:47]
	v_add_f32_e32 v94, v104, v103
	v_add_f32_e32 v95, v111, v110
	v_add_f32_e32 v94, v95, v94
	v_add_f32_e32 v106, v94, v81
	v_max_f32_e32 v81, v113, v113
	v_max_f32_e32 v94, v112, v112
	v_max_f32_e32 v81, v94, v81
	s_waitcnt lgkmcnt(2)
	v_mfma_f32_32x32x16_bf16 v[16:31], v[132:135], v[90:93], v[16:31]
	ds_read_b64_tr_b16 v[94:95], v213 offset:49152
	ds_read_b64_tr_b16 v[96:97], v213 offset:51200
	v_max3_f32 v81, v81, v114, v115
	v_max3_f32 v81, v81, v116, v117
	v_max3_f32 v81, v81, v118, v119
	v_max3_f32 v81, v81, v120, v121
	v_max3_f32 v81, v81, v122, v123
	v_max3_f32 v81, v81, v124, v125
	s_waitcnt lgkmcnt(2)
	v_mfma_f32_32x32x16_bf16 v[0:15], v[86:89], v[90:93], v[0:15]
	ds_read_b64_tr_b16 v[86:87], v214 offset:49152
	ds_read_b64_tr_b16 v[88:89], v214 offset:51200
	ds_read_b64_tr_b16 v[90:91], v213 offset:53248
	ds_read_b64_tr_b16 v[92:93], v213 offset:55296
	v_max3_f32 v81, v81, v126, v127
	v_max3_f32 v81, v81, v216, v217
	v_max3_f32 v81, v81, v218, v219
	v_max3_f32 v81, v81, v220, v221
	v_max3_f32 v81, v81, v222, v223
	v_max3_f32 v81, v81, v224, v225
	s_waitcnt lgkmcnt(4)
	v_mfma_f32_32x32x16_bf16 v[48:63], v[94:97], v[82:85], v[48:63]
	ds_read_b64_tr_b16 v[94:95], v215 offset:49152
	ds_read_b64_tr_b16 v[96:97], v215 offset:51200
	ds_read_b64_tr_b16 v[98:99], v214 offset:53248
	ds_read_b64_tr_b16 v[100:101], v214 offset:55296
	v_max3_f32 v81, v81, v226, v227
	v_max3_f32 v81, v81, v228, v229
	v_max3_f32 v107, v81, v230, v231
	v_add_f32_e32 v196, v194, v106
	v_add_f32_e32 v197, v195, v107
	v_mov_b64_e32 v[144:145], v[216:217]
	s_waitcnt lgkmcnt(6)
	v_mfma_f32_32x32x16_bf16 v[32:47], v[86:89], v[82:85], v[32:47]
	ds_read_b64_tr_b16 v[86:87], v248 offset:49152
	ds_read_b64_tr_b16 v[88:89], v248 offset:51200
	ds_read_b64_tr_b16 v[102:103], v215 offset:53248
	ds_read_b64_tr_b16 v[104:105], v215 offset:55296
	s_waitcnt lgkmcnt(6)
	v_mfma_f32_32x32x16_bf16 v[16:31], v[94:97], v[82:85], v[16:31]
	ds_read_b64_tr_b16 v[94:95], v248 offset:53248
	ds_read_b64_tr_b16 v[96:97], v248 offset:55296
	s_waitcnt vmcnt(0)
	s_waitcnt lgkmcnt(4)
	v_mfma_f32_32x32x16_bf16 v[0:15], v[86:89], v[82:85], v[0:15]
	v_cvt_pk_bf16_f32 v85, v110, v111
	v_cvt_pk_bf16_f32 v84, v108, v109
	v_cvt_pk_bf16_f32 v83, v138, v139
	v_cvt_pk_bf16_f32 v82, v136, v137
	s_nop 1
	v_mfma_f32_32x32x16_bf16 v[48:63], v[90:93], v[82:85], v[48:63]
	s_waitcnt lgkmcnt(0)
	s_barrier
	v_mfma_f32_32x32x16_bf16 v[32:47], v[98:101], v[82:85], v[32:47]
	s_cmp_gt_u32 s4, 33
	s_cselect_b64 s[6:7], -1, 0
	s_cmp_lt_u32 s4, 34
	s_cselect_b32 s20, s75, 0x230000
	v_mfma_f32_32x32x16_bf16 v[16:31], v[102:105], v[82:85], v[16:31]
	s_lshl_b64 s[8:9], s[20:21], 1
	s_add_u32 s8, s36, s8
	s_addc_u32 s9, s37, s9
	s_add_i32 s5, s77, 0
	v_mfma_f32_32x32x16_bf16 v[0:15], v[94:97], v[82:85], v[0:15]
	s_cbranch_vccnz .LBB0_432
.LBB0_424:
	v_add_u32_e32 v86, s76, v206
	ds_read_b128 v[82:85], v86
	ds_read_b128 v[86:89], v86 offset:4096
	v_lshl_add_u64 v[80:81], v[180:181], 1, s[8:9]
	s_add_i32 s8, s5, s42
	s_mov_b32 m0, s8
	s_nop 0
	global_load_lds_dwordx4 v[80:81], off
	v_lshl_add_u64 v[80:81], v[176:177], 1, s[38:39]
	s_mov_b32 m0, s67
	s_nop 0
	global_load_lds_dwordx4 v[80:81], off
	v_lshl_add_u64 v[80:81], v[178:179], 1, s[38:39]
	s_mov_b32 m0, s68
	s_nop 0
	global_load_lds_dwordx4 v[80:81], off
	v_add_f32_e32 v81, 0x41000000, v195
	v_cmp_gt_f32_e32 vcc, v197, v81
	s_cbranch_vccz .LBB0_428
	s_waitcnt lgkmcnt(0)
	ds_bpermute_b32 v80, v204, v197
	v_max_f32_e32 v82, v197, v197
	s_waitcnt lgkmcnt(0)
	v_max_f32_e32 v80, v80, v80
	v_max_f32_e32 v80, v82, v80
	v_mov_b64_e32 v[96:97], v[78:79]
	v_cmp_gt_f32_e32 vcc, v80, v81
	v_mov_b64_e32 v[94:95], v[76:77]
	v_mov_b64_e32 v[92:93], v[74:75]
	v_mov_b64_e32 v[90:91], v[72:73]
	v_mov_b64_e32 v[88:89], v[70:71]
	v_mov_b64_e32 v[86:87], v[68:69]
	v_mov_b64_e32 v[84:85], v[66:67]
	v_mov_b64_e32 v[82:83], v[64:65]
	s_and_saveexec_b64 s[8:9], vcc
	s_cbranch_execz .LBB0_427
	v_sub_f32_e32 v65, v80, v195
	v_exp_f32_e64 v64, -v65
	v_xor_b32_e32 v82, 0x80000000, v80
	v_sub_f32_e32 v127, v127, v65
	v_sub_f32_e32 v126, v126, v65
	v_mul_f32_e32 v196, v196, v64
	v_pk_mul_f32 v[62:63], v[62:63], v[64:65] op_sel_hi:[1,0]
	v_pk_mul_f32 v[60:61], v[60:61], v[64:65] op_sel_hi:[1,0]
	v_pk_mul_f32 v[58:59], v[58:59], v[64:65] op_sel_hi:[1,0]
	v_pk_mul_f32 v[56:57], v[56:57], v[64:65] op_sel_hi:[1,0]
	v_pk_mul_f32 v[54:55], v[54:55], v[64:65] op_sel_hi:[1,0]
	v_pk_mul_f32 v[52:53], v[52:53], v[64:65] op_sel_hi:[1,0]
	v_pk_mul_f32 v[50:51], v[50:51], v[64:65] op_sel_hi:[1,0]
	v_pk_mul_f32 v[48:49], v[48:49], v[64:65] op_sel_hi:[1,0]
	v_pk_mul_f32 v[46:47], v[46:47], v[64:65] op_sel_hi:[1,0]
	v_pk_mul_f32 v[44:45], v[44:45], v[64:65] op_sel_hi:[1,0]
	v_pk_mul_f32 v[42:43], v[42:43], v[64:65] op_sel_hi:[1,0]
	v_pk_mul_f32 v[40:41], v[40:41], v[64:65] op_sel_hi:[1,0]
	v_pk_mul_f32 v[38:39], v[38:39], v[64:65] op_sel_hi:[1,0]
	v_pk_mul_f32 v[36:37], v[36:37], v[64:65] op_sel_hi:[1,0]
	v_pk_mul_f32 v[34:35], v[34:35], v[64:65] op_sel_hi:[1,0]
	v_pk_mul_f32 v[32:33], v[32:33], v[64:65] op_sel_hi:[1,0]
	v_pk_mul_f32 v[30:31], v[30:31], v[64:65] op_sel_hi:[1,0]
	v_pk_mul_f32 v[28:29], v[28:29], v[64:65] op_sel_hi:[1,0]
	v_pk_mul_f32 v[26:27], v[26:27], v[64:65] op_sel_hi:[1,0]
	v_pk_mul_f32 v[24:25], v[24:25], v[64:65] op_sel_hi:[1,0]
	v_pk_mul_f32 v[22:23], v[22:23], v[64:65] op_sel_hi:[1,0]
	v_pk_mul_f32 v[20:21], v[20:21], v[64:65] op_sel_hi:[1,0]
	v_pk_mul_f32 v[18:19], v[18:19], v[64:65] op_sel_hi:[1,0]
	v_pk_mul_f32 v[16:17], v[16:17], v[64:65] op_sel_hi:[1,0]
	v_pk_mul_f32 v[14:15], v[14:15], v[64:65] op_sel_hi:[1,0]
	v_pk_mul_f32 v[12:13], v[12:13], v[64:65] op_sel_hi:[1,0]
	v_pk_mul_f32 v[10:11], v[10:11], v[64:65] op_sel_hi:[1,0]
	v_pk_mul_f32 v[8:9], v[8:9], v[64:65] op_sel_hi:[1,0]
	v_pk_mul_f32 v[6:7], v[6:7], v[64:65] op_sel_hi:[1,0]
	v_pk_mul_f32 v[4:5], v[4:5], v[64:65] op_sel_hi:[1,0]
	v_pk_mul_f32 v[2:3], v[2:3], v[64:65] op_sel_hi:[1,0]
	v_pk_mul_f32 v[0:1], v[0:1], v[64:65] op_sel_hi:[1,0]
	v_sub_f32_e32 v125, v125, v65
	v_sub_f32_e32 v124, v124, v65
	v_sub_f32_e32 v123, v123, v65
	v_sub_f32_e32 v122, v122, v65
	v_sub_f32_e32 v121, v121, v65
	v_sub_f32_e32 v120, v120, v65
	v_sub_f32_e32 v119, v119, v65
	v_sub_f32_e32 v118, v118, v65
	v_sub_f32_e32 v117, v117, v65
	v_sub_f32_e32 v116, v116, v65
	v_sub_f32_e32 v115, v115, v65
	v_sub_f32_e32 v114, v114, v65
	v_sub_f32_e32 v113, v113, v65
	v_sub_f32_e32 v112, v112, v65
	v_sub_f32_e32 v159, v159, v65
	v_sub_f32_e32 v158, v158, v65
	v_sub_f32_e32 v157, v157, v65
	v_sub_f32_e32 v156, v156, v65
	v_sub_f32_e32 v155, v155, v65
	v_sub_f32_e32 v154, v154, v65
	v_sub_f32_e32 v153, v153, v65
	v_sub_f32_e32 v152, v152, v65
	v_sub_f32_e32 v151, v151, v65
	v_sub_f32_e32 v150, v150, v65
	v_sub_f32_e32 v149, v149, v65
	v_sub_f32_e32 v148, v148, v65
	v_sub_f32_e32 v147, v147, v65
	v_sub_f32_e32 v146, v146, v65
	v_sub_f32_e32 v145, v145, v65
	v_sub_f32_e32 v144, v144, v65
	v_add_f32_e32 v81, 0x41000000, v80
	v_mov_b32_e32 v83, v82
	v_mov_b32_e32 v84, v82
	v_mov_b32_e32 v85, v82
	v_mov_b32_e32 v86, v82
	v_mov_b32_e32 v87, v82
	v_mov_b32_e32 v88, v82
	v_mov_b32_e32 v89, v82
	v_mov_b32_e32 v90, v82
	v_mov_b32_e32 v91, v82
	v_mov_b32_e32 v92, v82
	v_mov_b32_e32 v93, v82
	v_mov_b32_e32 v94, v82
	v_mov_b32_e32 v95, v82
	v_mov_b32_e32 v96, v82
	v_mov_b32_e32 v97, v82
	v_mov_b32_e32 v79, v82
	v_mov_b32_e32 v78, v82
	v_mov_b32_e32 v77, v82
	v_mov_b32_e32 v76, v82
	v_mov_b32_e32 v75, v82
	v_mov_b32_e32 v74, v82
	v_mov_b32_e32 v73, v82
	v_mov_b32_e32 v72, v82
	v_mov_b32_e32 v71, v82
	v_mov_b32_e32 v70, v82
	v_mov_b32_e32 v69, v82
	v_mov_b32_e32 v68, v82
	v_mov_b32_e32 v67, v82
	v_mov_b32_e32 v66, v82
	v_mov_b32_e32 v65, v82
	v_mov_b32_e32 v64, v82
	v_mov_b32_e32 v195, v80
